# QK->PV serial chain shortened in both attention loops: p1 row-max as depth-3 v_max3 tree, v_max x,x,x canonicalisations dropped, -m*c multiply hoisted into the MFMA->VALU wait (recomputed on the new-m
# baseline (speedup 1.0000x reference)
; #define SBAR() __builtin_amdgcn_sched_barrier(0)
; __device__ __forceinline__ int crow(int r, int hi) { return (r & 3) + 8 * (r >> 2) + 4 * hi; }
; __device__ __forceinline__ float qkt_deep(f32x16& p0, f32x16& p1, const int (&ka)[4], const bf16x8 (&qr)[8]) {
;     ...
;   QD_RD0(0); QD_RD0(1); QD_RD0(2); QD_RD0(3); QD_RD0(4); QD_RD0(5); QD_RD0(6); QD_RD0(7);
;   QK_WAIT(7); QD_MM0(0); SBAR(); QD_RD1(0);
;   QK_WAIT(7); QD_MM0(1); SBAR(); QD_RD1(1);
;   QK_WAIT(7); QD_MM0(2); SBAR(); QD_RD1(2);
;   QK_WAIT(7); QD_MM0(3); SBAR(); QD_RD1(3);
;   QK_WAIT(7); QD_MM0(4); SBAR(); QD_RD1(4);
;   QK_WAIT(7); QD_MM0(5); SBAR(); QD_RD1(5);
;   QK_WAIT(7); QD_MM0(6); SBAR(); QD_RD1(6);
;   QK_WAIT(7); QD_MM0(7); SBAR(); QD_RD1(7);
;   QK_WAIT(7); QD_MM1(0); pm = fmaxf(p0[0], p0[1]); SBAR();
;   QK_WAIT(6); QD_MM1(1); pm = fmaxf(fmaxf(pm, p0[2]), p0[3]); SBAR();
;   QK_WAIT(5); QD_MM1(2); pm = fmaxf(fmaxf(pm, p0[4]), p0[5]); SBAR();
;   QK_WAIT(4); QD_MM1(3); pm = fmaxf(fmaxf(pm, p0[6]), p0[7]); SBAR();
;   QK_WAIT(3); QD_MM1(4); pm = fmaxf(fmaxf(pm, p0[8]), p0[9]); SBAR();
;   QK_WAIT(2); QD_MM1(5); pm = fmaxf(fmaxf(pm, p0[10]), p0[11]); SBAR();
;   QK_WAIT(1); QD_MM1(6); pm = fmaxf(fmaxf(pm, p0[12]), p0[13]); SBAR();
;   QK_WAIT(0); QD_MM1(7); pm = fmaxf(fmaxf(pm, p0[14]), p0[15]);
;   return pm;
; }
; template <int LD>
; __device__ __forceinline__ void attn256_body(const bf16_t* __restrict__ Qb, const bf16_t* __restrict__ Kh, const unsigned char* __restrict__ Vimg, int seq, char* lds, LAS unsigned char* ldsl,
;                                              f32x16 (&o)[8], float (&rli)[16]) {
;     ...
; #pragma unroll
;     for (int r = 0; r < 16; ++r) pmax = fmaxf(pmax, p1[r]);
;     pmax = half_swap_max(pmax);
;     float mn, alpha;
;     if (__builtin_expect(__all(pmax - m_reg <= ATT_THR / ATT_SCALE), 1)) { mn = m_reg; alpha = 1.f; }
;     else { mn = fmaxf(m_reg, pmax); alpha = __builtin_amdgcn_exp2f((m_reg - mn) * C); m_reg = mn; }
;     const float mnC = -mn * C; float ps;
;     if (__any(alpha < 1.f)) { if (hi == 0) al_l[r32] = alpha; asm volatile("s_waitcnt lgkmcnt(0)" ::: "memory");
; #pragma unroll
;       for (int d = 0; d < 8; ++d)
; #pragma unroll
;         for (int r = 0; r < 16; ++r) o[d][r] *= al_l[crow(r, hi)]; }
;     const int vb = vb0 + cur * A2_STAGE;
;     exp_pv256(o, p0, p1, vb, C, mnC, ps);
.LBB0_663:
	s_mul_i32 s4, s4, 0xc000
	s_waitcnt lgkmcnt(0)
	v_add_u32_e32 v0, s4, v221
	v_add_u32_e32 v14, v0, v233
	v_add_u32_e32 v15, v0, v234
	v_add_u32_e32 v252, v0, v235
	v_add_u32_e32 v0, v0, v236
	ds_read_b128 v[2:5], v14 offset:0
	ds_read_b128 v[6:9], v15 offset:0
	ds_read_b128 v[10:13], v252 offset:0
	ds_read_b128 v[144:147], v0 offset:0
	ds_read_b128 v[148:151], v14 offset:0x80
	ds_read_b128 v[152:155], v15 offset:0x80
	ds_read_b128 v[156:159], v252 offset:0x80
	ds_read_b128 v[208:211], v0 offset:0x80
	s_waitcnt lgkmcnt(7)
	s_nop 0
	v_mfma_f32_32x32x16_bf16 v[160:175], v[2:5], v[176:179], 0
	ds_read_b128 v[2:5], v14 offset:0x2000
	s_waitcnt lgkmcnt(7)
	s_nop 0
	v_mfma_f32_32x32x16_bf16 v[160:175], v[6:9], v[180:183], v[160:175]
	ds_read_b128 v[6:9], v15 offset:0x2000
	s_waitcnt lgkmcnt(7)
	s_nop 0
	v_mfma_f32_32x32x16_bf16 v[160:175], v[10:13], v[184:187], v[160:175]
	ds_read_b128 v[10:13], v252 offset:0x2000
	s_waitcnt lgkmcnt(7)
	s_nop 0
	v_mfma_f32_32x32x16_bf16 v[160:175], v[144:147], v[188:191], v[160:175]
	ds_read_b128 v[240:243], v0 offset:0x2000
	s_waitcnt lgkmcnt(7)
	s_nop 0
	v_mfma_f32_32x32x16_bf16 v[160:175], v[148:151], v[192:195], v[160:175]
	ds_read_b128 v[244:247], v14 offset:0x2080
	s_waitcnt lgkmcnt(7)
	s_nop 0
	v_mfma_f32_32x32x16_bf16 v[160:175], v[152:155], v[196:199], v[160:175]
	ds_read_b128 v[248:251], v15 offset:0x2080
	s_waitcnt lgkmcnt(7)
	s_nop 0
	v_mfma_f32_32x32x16_bf16 v[160:175], v[156:159], v[200:203], v[160:175]
	ds_read_b128 v[212:215], v252 offset:0x2080
	s_waitcnt lgkmcnt(7)
	s_nop 0
	v_mfma_f32_32x32x16_bf16 v[160:175], v[208:211], v[204:207], v[160:175]
	ds_read_b128 v[208:211], v0 offset:0x2080
	s_waitcnt lgkmcnt(7)
	v_mfma_f32_32x32x16_bf16 v[144:159], v[2:5], v[176:179], 0
	s_nop 10
	v_max_f32_e32 v0, v161, v161
	v_max_f32_e32 v2, v160, v160
	v_max_f32_e32 v0, v2, v0
	s_waitcnt lgkmcnt(6)
	s_nop 0
	v_mfma_f32_32x32x16_bf16 v[144:159], v[6:9], v[180:183], v[144:159]
	v_max3_f32 v0, v0, v162, v163
	s_waitcnt lgkmcnt(5)
	s_nop 0
	v_mfma_f32_32x32x16_bf16 v[144:159], v[10:13], v[184:187], v[144:159]
	v_max3_f32 v0, v0, v164, v165
	s_waitcnt lgkmcnt(4)
	s_nop 0
	v_mfma_f32_32x32x16_bf16 v[144:159], v[240:243], v[188:191], v[144:159]
	v_max3_f32 v0, v0, v166, v167
	s_waitcnt lgkmcnt(3)
	s_nop 0
	v_mfma_f32_32x32x16_bf16 v[144:159], v[244:247], v[192:195], v[144:159]
	v_max3_f32 v0, v0, v168, v169
	s_waitcnt lgkmcnt(2)
	s_nop 0
	v_mfma_f32_32x32x16_bf16 v[144:159], v[248:251], v[196:199], v[144:159]
	v_max3_f32 v0, v0, v170, v171
	s_waitcnt lgkmcnt(1)
	s_nop 0
	v_mfma_f32_32x32x16_bf16 v[144:159], v[212:215], v[200:203], v[144:159]
	v_max3_f32 v0, v0, v172, v173
	s_waitcnt lgkmcnt(0)
	s_nop 0
	v_mfma_f32_32x32x16_bf16 v[144:159], v[208:211], v[204:207], v[144:159]
	v_max3_f32 v0, v0, v174, v175
	v_mul_f32_e32 v14, 0xbe0293ee, v238
	s_nop 9
	v_max3_f32 v2, v144, v145, v146
	v_max3_f32 v3, v147, v148, v149
	v_max3_f32 v4, v150, v151, v152
	v_max3_f32 v5, v153, v154, v155
	v_max3_f32 v6, v156, v157, v158
	v_max3_f32 v2, v2, v3, v4
	v_max3_f32 v5, v5, v6, v159
	v_max3_f32 v0, v0, v2, v5
	v_mov_b32_e32 v2, v0
	s_nop 1
	v_permlane32_swap_b32_e32 v0, v2
	v_max_f32_e32 v2, v0, v2
	v_sub_f32_e32 v0, v2, v238
	v_cmp_ge_f32_e32 vcc, s93, v0
	s_cmp_eq_u64 vcc, exec
	v_mov_b32_e32 v0, 1.0
	s_cbranch_scc0 .LBB0_670
.LBB0_668:
	v_fmamk_f32 v2, v160, 0x3e0293ee, v14
	v_exp_f32_e32 v2, v2
	v_fmamk_f32 v3, v161, 0x3e0293ee, v14
	v_exp_f32_e32 v3, v3
	v_fmamk_f32 v4, v162, 0x3e0293ee, v14
	v_exp_f32_e32 v4, v4
	v_fmamk_f32 v5, v163, 0x3e0293ee, v14
	v_exp_f32_e32 v5, v5
	v_fmamk_f32 v7, v164, 0x3e0293ee, v14
	v_add_f32_e32 v6, 0, v2
	v_exp_f32_e32 v7, v7
	v_fmamk_f32 v8, v165, 0x3e0293ee, v14
	v_add_f32_e32 v6, v3, v6
	v_exp_f32_e32 v8, v8
	v_fmamk_f32 v9, v166, 0x3e0293ee, v14
	v_add_f32_e32 v6, v4, v6
	v_exp_f32_e32 v9, v9
	v_fmamk_f32 v10, v167, 0x3e0293ee, v14
	v_add_f32_e32 v6, v5, v6
	v_exp_f32_e32 v10, v10
	v_add_f32_e32 v6, v7, v6
	v_cvt_pk_bf16_f32 v2, v2, v3
	v_cvt_pk_bf16_f32 v3, v4, v5
	v_cvt_pk_bf16_f32 v4, v7, v8
	v_cvt_pk_bf16_f32 v5, v9, v10
	s_waitcnt lgkmcnt(0)
	v_add_f32_e32 v6, v8, v6
	s_add_i32 s45, s45, 1
	v_add_f32_e32 v6, v9, v6
	v_permlane32_swap_b32_e32 v2, v4
	v_add_u32_e32 v15, s4, v237
	v_add_f32_e32 v248, v10, v6
	v_permlane32_swap_b32_e32 v3, v5
	ds_read_b64_tr_b16 v[6:7], v15 offset:0
	ds_read_b64_tr_b16 v[8:9], v15 offset:0x800
	ds_read_b64_tr_b16 v[10:11], v15 offset:0x200
	ds_read_b64_tr_b16 v[12:13], v15 offset:0xa00
	ds_read_b64_tr_b16 v[160:161], v15 offset:0x400
	ds_read_b64_tr_b16 v[162:163], v15 offset:0xc00
	ds_read_b64_tr_b16 v[164:165], v15 offset:0x600
	ds_read_b64_tr_b16 v[166:167], v15 offset:0xe00
	v_add_u32_e32 v249, 0x4000, v15
	ds_read_b64_tr_b16 v[208:209], v249 offset:0
	ds_read_b64_tr_b16 v[210:211], v249 offset:0x800
	ds_read_b64_tr_b16 v[212:213], v249 offset:0x200
	ds_read_b64_tr_b16 v[214:215], v249 offset:0xa00
	ds_read_b64_tr_b16 v[240:241], v249 offset:0x400
	ds_read_b64_tr_b16 v[242:243], v249 offset:0xc00
	ds_read_b64_tr_b16 v[244:245], v249 offset:0x600
	ds_read_b64_tr_b16 v[246:247], v249 offset:0xe00
	s_waitcnt lgkmcnt(8)
	s_nop 0
	v_mfma_f32_32x32x16_bf16 v[128:143], v[2:5], v[6:9], v[128:143]
	v_fmamk_f32 v6, v168, 0x3e0293ee, v14
	v_exp_f32_e32 v168, v6
	v_fmamk_f32 v6, v169, 0x3e0293ee, v14
	v_exp_f32_e32 v169, v6
	v_fmamk_f32 v6, v170, 0x3e0293ee, v14
	v_exp_f32_e32 v170, v6
	v_fmamk_f32 v6, v171, 0x3e0293ee, v14
	v_mfma_f32_32x32x16_bf16 v[112:127], v[2:5], v[10:13], v[112:127]
	v_exp_f32_e32 v171, v6
	v_add_f32_e32 v6, v168, v248
	v_add_f32_e32 v6, v169, v6
	v_add_f32_e32 v6, v170, v6
	v_add_f32_e32 v248, v171, v6
	v_mfma_f32_32x32x16_bf16 v[96:111], v[2:5], v[160:163], v[96:111]
	v_mfma_f32_32x32x16_bf16 v[80:95], v[2:5], v[164:167], v[80:95]
	ds_read_b64_tr_b16 v[6:7], v15 offset:0x1000
	ds_read_b64_tr_b16 v[8:9], v15 offset:0x1800
	ds_read_b64_tr_b16 v[10:11], v15 offset:0x1200
	ds_read_b64_tr_b16 v[12:13], v15 offset:0x1a00
	ds_read_b64_tr_b16 v[160:161], v15 offset:0x1400
	ds_read_b64_tr_b16 v[162:163], v15 offset:0x1c00
	ds_read_b64_tr_b16 v[164:165], v15 offset:0x1600
	ds_read_b64_tr_b16 v[166:167], v15 offset:0x1e00
	s_waitcnt lgkmcnt(8)
; #define SBAR() __builtin_amdgcn_sched_barrier(0)
; __device__ __forceinline__ float half_swap_sum(float v) { auto rr = __builtin_amdgcn_permlane32_swap(__float_as_uint(v), __float_as_uint(v), false, false); return __uint_as_float(rr[0]) + __uint_as_float(rr[1]); }
; #define LGKM_WAIT8() do { asm volatile("s_waitcnt lgkmcnt(8)" ::: "memory"); SBAR(); } while (0)
; #define LGKM_WAIT0() do { asm volatile("s_waitcnt lgkmcnt(0)" ::: "memory"); SBAR(); } while (0)
; #define EX4(P, B) do { _Pragma("unroll") for (int r_ = (B); r_ < (B) + 4; ++r_) { P[r_] = __builtin_amdgcn_exp2f(fmaf(P[r_], C, mnC)); ps += P[r_]; } } while (0)
; __device__ __forceinline__ void exp_pv256(f32x16 (&o)[8], f32x16& p0, f32x16& p1, int vb, float C, float mnC, float& ps) {
;     ...
;   EX4(p0, 0); EX4(p0, 4); pa = pk4<0>(p0);
;   asm volatile("s_waitcnt lgkmcnt(0)" ::: "memory"); SBAR();
;   vg4_read<0>(fa, vb); vg4_read<0>(fb, vb + 16384);
;   LGKM_WAIT8(); vg4_mma<0>(o, fa, pa); EX4(p0, 8); SBAR();
;   vg4_read<1>(fa, vb); LGKM_WAIT8(); vg4_mma<1>(o, fb, pa); EX4(p0, 12); pn = pk4<8>(p0); SBAR();
;   vg4_read<1>(fb, vb + 16384); LGKM_WAIT8(); vg4_mma<0>(o, fa, pn); EX4(p1, 0); SBAR();
;   vg4_read<2>(fa, vb); LGKM_WAIT8(); vg4_mma<1>(o, fb, pn); EX4(p1, 4); pa = pk4<0>(p1); SBAR();
;   vg4_read<2>(fb, vb + 16384); LGKM_WAIT8(); vg4_mma<0>(o, fa, pa); EX4(p1, 8); SBAR();
;   vg4_read<3>(fa, vb); LGKM_WAIT8(); vg4_mma<1>(o, fb, pa); EX4(p1, 12); pn = pk4<8>(p1); SBAR();
;   vg4_read<3>(fb, vb + 16384); LGKM_WAIT8(); vg4_mma<0>(o, fa, pn); SBAR();
;   LGKM_WAIT0(); vg4_mma<1>(o, fb, pn);
; template <int LD>
; __device__ __forceinline__ void attn256_body(const bf16_t* __restrict__ Qb, const bf16_t* __restrict__ Kh, const unsigned char* __restrict__ Vimg, int seq, char* lds, LAS unsigned char* ldsl,
;                                              f32x16 (&o)[8], float (&rli)[16]) {
;     ...
;     ps = half_swap_sum(ps);
;     l_reg = l_reg * alpha + ps;
;     asm volatile("s_waitcnt vmcnt(0)" ::: "memory"); __syncthreads();
;   }
	v_mfma_f32_32x32x16_bf16 v[64:79], v[2:5], v[208:211], v[64:79]
	v_fmamk_f32 v172, v172, 0x3e0293ee, v14
	v_exp_f32_e32 v172, v172
	v_fmamk_f32 v173, v173, 0x3e0293ee, v14
	v_exp_f32_e32 v173, v173
	v_fmamk_f32 v174, v174, 0x3e0293ee, v14
	v_exp_f32_e32 v174, v174
	v_fmamk_f32 v175, v175, 0x3e0293ee, v14
	v_mfma_f32_32x32x16_bf16 v[48:63], v[2:5], v[212:215], v[48:63]
	v_exp_f32_e32 v175, v175
	v_add_f32_e32 v208, v172, v248
	v_add_f32_e32 v208, v173, v208
	v_add_f32_e32 v208, v174, v208
	v_cvt_pk_bf16_f32 v168, v168, v169
	v_cvt_pk_bf16_f32 v169, v170, v171
	v_cvt_pk_bf16_f32 v170, v172, v173
	v_mfma_f32_32x32x16_bf16 v[32:47], v[2:5], v[240:243], v[32:47]
	v_cvt_pk_bf16_f32 v171, v174, v175
	v_add_f32_e32 v248, v175, v208
	v_permlane32_swap_b32_e32 v168, v170
	v_permlane32_swap_b32_e32 v169, v171
	v_mfma_f32_32x32x16_bf16 v[16:31], v[2:5], v[244:247], v[16:31]
	ds_read_b64_tr_b16 v[2:3], v249 offset:0x1000
	ds_read_b64_tr_b16 v[4:5], v249 offset:0x1800
	ds_read_b64_tr_b16 v[172:173], v249 offset:0x1200
	ds_read_b64_tr_b16 v[174:175], v249 offset:0x1a00
	ds_read_b64_tr_b16 v[208:209], v249 offset:0x1400
	ds_read_b64_tr_b16 v[210:211], v249 offset:0x1c00
	ds_read_b64_tr_b16 v[212:213], v249 offset:0x1600
	ds_read_b64_tr_b16 v[214:215], v249 offset:0x1e00
	s_waitcnt lgkmcnt(8)
	s_nop 0
	v_mfma_f32_32x32x16_bf16 v[128:143], v[168:171], v[6:9], v[128:143]
	v_fmamk_f32 v6, v144, 0x3e0293ee, v14
	v_exp_f32_e32 v240, v6
	v_fmamk_f32 v6, v145, 0x3e0293ee, v14
	v_exp_f32_e32 v241, v6
	v_fmamk_f32 v6, v146, 0x3e0293ee, v14
	v_exp_f32_e32 v242, v6
	v_fmamk_f32 v6, v147, 0x3e0293ee, v14
	v_mfma_f32_32x32x16_bf16 v[112:127], v[168:171], v[10:13], v[112:127]
	v_exp_f32_e32 v243, v6
	v_add_f32_e32 v6, v240, v248
	v_add_f32_e32 v6, v241, v6
	v_add_f32_e32 v6, v242, v6
	v_add_f32_e32 v244, v243, v6
	v_mfma_f32_32x32x16_bf16 v[96:111], v[168:171], v[160:163], v[96:111]
	v_mfma_f32_32x32x16_bf16 v[80:95], v[168:171], v[164:167], v[80:95]
	ds_read_b64_tr_b16 v[6:7], v15 offset:0x2000
	ds_read_b64_tr_b16 v[8:9], v15 offset:0x2800
	ds_read_b64_tr_b16 v[10:11], v15 offset:0x2200
	ds_read_b64_tr_b16 v[12:13], v15 offset:0x2a00
	ds_read_b64_tr_b16 v[144:145], v15 offset:0x2400
	ds_read_b64_tr_b16 v[146:147], v15 offset:0x2c00
	ds_read_b64_tr_b16 v[160:161], v15 offset:0x2600
	ds_read_b64_tr_b16 v[162:163], v15 offset:0x2e00
	s_waitcnt lgkmcnt(8)
	v_mfma_f32_32x32x16_bf16 v[64:79], v[168:171], v[2:5], v[64:79]
	v_fmamk_f32 v2, v148, 0x3e0293ee, v14
	v_exp_f32_e32 v4, v2
	v_fmamk_f32 v2, v149, 0x3e0293ee, v14
	v_exp_f32_e32 v5, v2
	v_fmamk_f32 v2, v150, 0x3e0293ee, v14
	v_exp_f32_e32 v148, v2
	v_fmamk_f32 v2, v151, 0x3e0293ee, v14
	v_mfma_f32_32x32x16_bf16 v[48:63], v[168:171], v[172:175], v[48:63]
	v_exp_f32_e32 v149, v2
	v_add_f32_e32 v2, v4, v244
	v_add_f32_e32 v2, v5, v2
	v_add_f32_e32 v2, v148, v2
	v_add_f32_e32 v244, v149, v2
	v_cvt_pk_bf16_f32 v2, v240, v241
	v_cvt_pk_bf16_f32 v3, v242, v243
	v_mfma_f32_32x32x16_bf16 v[32:47], v[168:171], v[208:211], v[32:47]
	v_cvt_pk_bf16_f32 v4, v4, v5
	v_cvt_pk_bf16_f32 v5, v148, v149
	s_nop 0
	v_permlane32_swap_b32_e32 v2, v4
	v_permlane32_swap_b32_e32 v3, v5
	v_mfma_f32_32x32x16_bf16 v[16:31], v[168:171], v[212:215], v[16:31]
	ds_read_b64_tr_b16 v[148:149], v249 offset:0x2000
	ds_read_b64_tr_b16 v[150:151], v249 offset:0x2800
	ds_read_b64_tr_b16 v[164:165], v249 offset:0x2200
	ds_read_b64_tr_b16 v[166:167], v249 offset:0x2a00
	ds_read_b64_tr_b16 v[168:169], v249 offset:0x2400
	ds_read_b64_tr_b16 v[170:171], v249 offset:0x2c00
	ds_read_b64_tr_b16 v[172:173], v249 offset:0x2600
	ds_read_b64_tr_b16 v[174:175], v249 offset:0x2e00
	s_waitcnt lgkmcnt(8)
	s_nop 0
	v_mfma_f32_32x32x16_bf16 v[128:143], v[2:5], v[6:9], v[128:143]
	v_fmamk_f32 v6, v152, 0x3e0293ee, v14
	v_exp_f32_e32 v208, v6
	v_fmamk_f32 v6, v153, 0x3e0293ee, v14
	v_exp_f32_e32 v209, v6
	v_fmamk_f32 v6, v154, 0x3e0293ee, v14
	v_exp_f32_e32 v210, v6
	v_fmamk_f32 v6, v155, 0x3e0293ee, v14
	v_mfma_f32_32x32x16_bf16 v[112:127], v[2:5], v[10:13], v[112:127]
	v_exp_f32_e32 v211, v6
	v_add_f32_e32 v6, v208, v244
	v_add_f32_e32 v6, v209, v6
	v_add_f32_e32 v6, v210, v6
	v_add_f32_e32 v212, v211, v6
	v_mfma_f32_32x32x16_bf16 v[96:111], v[2:5], v[144:147], v[96:111]
	v_mfma_f32_32x32x16_bf16 v[80:95], v[2:5], v[160:163], v[80:95]
	ds_read_b64_tr_b16 v[6:7], v15 offset:0x3000
	ds_read_b64_tr_b16 v[8:9], v15 offset:0x3800
	ds_read_b64_tr_b16 v[10:11], v15 offset:0x3200
	ds_read_b64_tr_b16 v[12:13], v15 offset:0x3a00
	ds_read_b64_tr_b16 v[144:145], v15 offset:0x3400
	ds_read_b64_tr_b16 v[146:147], v15 offset:0x3c00
	ds_read_b64_tr_b16 v[152:153], v15 offset:0x3600
	ds_read_b64_tr_b16 v[154:155], v15 offset:0x3e00
	s_waitcnt lgkmcnt(8)
	v_fmamk_f32 v15, v156, 0x3e0293ee, v14
	v_mfma_f32_32x32x16_bf16 v[64:79], v[2:5], v[148:151], v[64:79]
	v_exp_f32_e32 v15, v15
	v_fmamk_f32 v148, v157, 0x3e0293ee, v14
	v_exp_f32_e32 v150, v148
	v_fmamk_f32 v148, v158, 0x3e0293ee, v14
	v_exp_f32_e32 v151, v148
	v_fmac_f32_e32 v14, 0x3e0293ee, v159
	v_exp_f32_e32 v14, v14
	v_mfma_f32_32x32x16_bf16 v[48:63], v[2:5], v[164:167], v[48:63]
	v_add_f32_e32 v148, v15, v212
	v_add_f32_e32 v148, v150, v148
	v_add_f32_e32 v148, v151, v148
	v_add_f32_e32 v212, v14, v148
	v_cvt_pk_bf16_f32 v148, v208, v209
	v_cvt_pk_bf16_f32 v149, v210, v211
	v_cvt_pk_bf16_f32 v150, v15, v150
	v_mfma_f32_32x32x16_bf16 v[32:47], v[2:5], v[168:171], v[32:47]
	v_cvt_pk_bf16_f32 v151, v151, v14
	v_permlane32_swap_b32_e32 v148, v150
	v_permlane32_swap_b32_e32 v149, v151
	v_mfma_f32_32x32x16_bf16 v[16:31], v[2:5], v[172:175], v[16:31]
	ds_read_b64_tr_b16 v[2:3], v249 offset:0x3000
	ds_read_b64_tr_b16 v[4:5], v249 offset:0x3800
	ds_read_b64_tr_b16 v[156:157], v249 offset:0x3200
	ds_read_b64_tr_b16 v[158:159], v249 offset:0x3a00
	ds_read_b64_tr_b16 v[160:161], v249 offset:0x3400
	ds_read_b64_tr_b16 v[162:163], v249 offset:0x3c00
	ds_read_b64_tr_b16 v[164:165], v249 offset:0x3600
	ds_read_b64_tr_b16 v[166:167], v249 offset:0x3e00
	s_waitcnt lgkmcnt(8)
	s_nop 0
	v_mfma_f32_32x32x16_bf16 v[128:143], v[148:151], v[6:9], v[128:143]
	v_mfma_f32_32x32x16_bf16 v[112:127], v[148:151], v[10:13], v[112:127]
	v_mfma_f32_32x32x16_bf16 v[96:111], v[148:151], v[144:147], v[96:111]
	v_mfma_f32_32x32x16_bf16 v[80:95], v[148:151], v[152:155], v[80:95]
	s_waitcnt lgkmcnt(0)
	v_mfma_f32_32x32x16_bf16 v[64:79], v[148:151], v[2:5], v[64:79]
	v_mov_b32_e32 v2, v212
	s_nop 1
	v_permlane32_swap_b32_e32 v212, v2
	s_waitcnt vmcnt(0)
	v_add_f32_e32 v2, v212, v2
	v_fmac_f32_e32 v2, v239, v0
	v_lshl_add_u64 v[222:223], v[222:223], 0, s[30:31]
	v_mfma_f32_32x32x16_bf16 v[48:63], v[148:151], v[156:159], v[48:63]
	v_lshl_add_u64 v[224:225], v[224:225], 0, s[26:27]
	v_lshl_add_u64 v[226:227], v[226:227], 0, s[26:27]
	v_mov_b32_e32 v239, v2
	s_and_b32 s4, s45, 1
	s_cmpk_eq_i32 s45, 0xff
	s_cselect_b64 vcc, -1, 0
	s_cmpk_eq_i32 s45, 0x100
	s_waitcnt vmcnt(0) lgkmcnt(0)
	s_barrier
; template <int LD>
; __device__ __forceinline__ void attn256_body(const bf16_t* __restrict__ Qb, const bf16_t* __restrict__ Kh, const unsigned char* __restrict__ Vimg, int seq, char* lds, LAS unsigned char* ldsl,
;                                              f32x16 (&o)[8], float (&rli)[16]) {
;     ...
;     if (__builtin_expect(__all(pmax - m_reg <= ATT_THR / ATT_SCALE), 1)) { mn = m_reg; alpha = 1.f; }
;     else { mn = fmaxf(m_reg, pmax); alpha = __builtin_amdgcn_exp2f((m_reg - mn) * C); m_reg = mn; }
;     const float mnC = -mn * C; float ps;
;     if (__any(alpha < 1.f)) { if (hi == 0) al_l[r32] = alpha; asm volatile("s_waitcnt lgkmcnt(0)" ::: "memory");
	v_mfma_f32_32x32x16_bf16 v[32:47], v[148:151], v[160:163], v[32:47]
	v_mfma_f32_32x32x16_bf16 v[16:31], v[148:151], v[164:167], v[16:31]
	s_cbranch_scc1 .LBB0_671
	s_cbranch_vccz .LBB0_662
	s_branch .LBB0_663
.LBB0_670:
	v_max_f32_e32 v0, v2, v2
	v_max_f32_e32 v2, v238, v238
	v_max_f32_e32 v2, v2, v0
	v_sub_f32_e32 v0, v238, v2
	v_mul_f32_e32 v0, 0x3e0293ee, v0
	v_exp_f32_e32 v0, v0
	v_mov_b32_e32 v238, v2
	v_mul_f32_e32 v14, 0xbe0293ee, v238
	v_cmp_gt_f32_e32 vcc, 1.0, v0
	s_cbranch_vccnz .LBB0_665
	s_branch .LBB0_668

; #define SBAR() __builtin_amdgcn_sched_barrier(0)
; __device__ __forceinline__ int crow(int r, int hi) { return (r & 3) + 8 * (r >> 2) + 4 * hi; }
; __device__ __forceinline__ float qkt_deep(f32x16& p0, f32x16& p1, const int (&ka)[4], const bf16x8 (&qr)[8]) {
;     ...
;   QD_RD0(0); QD_RD0(1); QD_RD0(2); QD_RD0(3); QD_RD0(4); QD_RD0(5); QD_RD0(6); QD_RD0(7);
;   QK_WAIT(7); QD_MM0(0); SBAR(); QD_RD1(0);
;   QK_WAIT(7); QD_MM0(1); SBAR(); QD_RD1(1);
;   QK_WAIT(7); QD_MM0(2); SBAR(); QD_RD1(2);
;   QK_WAIT(7); QD_MM0(3); SBAR(); QD_RD1(3);
;   QK_WAIT(7); QD_MM0(4); SBAR(); QD_RD1(4);
;   QK_WAIT(7); QD_MM0(5); SBAR(); QD_RD1(5);
;   QK_WAIT(7); QD_MM0(6); SBAR(); QD_RD1(6);
;   QK_WAIT(7); QD_MM0(7); SBAR(); QD_RD1(7);
;   QK_WAIT(7); QD_MM1(0); pm = fmaxf(p0[0], p0[1]); SBAR();
;   QK_WAIT(6); QD_MM1(1); pm = fmaxf(fmaxf(pm, p0[2]), p0[3]); SBAR();
;   QK_WAIT(5); QD_MM1(2); pm = fmaxf(fmaxf(pm, p0[4]), p0[5]); SBAR();
;   QK_WAIT(4); QD_MM1(3); pm = fmaxf(fmaxf(pm, p0[6]), p0[7]); SBAR();
;   QK_WAIT(3); QD_MM1(4); pm = fmaxf(fmaxf(pm, p0[8]), p0[9]); SBAR();
;   QK_WAIT(2); QD_MM1(5); pm = fmaxf(fmaxf(pm, p0[10]), p0[11]); SBAR();
;   QK_WAIT(1); QD_MM1(6); pm = fmaxf(fmaxf(pm, p0[12]), p0[13]); SBAR();
;   QK_WAIT(0); QD_MM1(7); pm = fmaxf(fmaxf(pm, p0[14]), p0[15]);
;   return pm;
; }
; template <int LD>
; __device__ __forceinline__ void attn256_body(const bf16_t* __restrict__ Qb, const bf16_t* __restrict__ Kh, const unsigned char* __restrict__ Vimg, int seq, char* lds, LAS unsigned char* ldsl,
;                                              f32x16 (&o)[8], float (&rli)[16]) {
;     ...
; #pragma unroll
;     for (int r = 0; r < 16; ++r) pmax = fmaxf(pmax, p1[r]);
;     pmax = half_swap_max(pmax);
;     float mn, alpha;
;     if (__builtin_expect(__all(pmax - m_reg <= ATT_THR / ATT_SCALE), 1)) { mn = m_reg; alpha = 1.f; }
;     else { mn = fmaxf(m_reg, pmax); alpha = __builtin_amdgcn_exp2f((m_reg - mn) * C); m_reg = mn; }
;     const float mnC = -mn * C; float ps;
;     if (__any(alpha < 1.f)) { if (hi == 0) al_l[r32] = alpha; asm volatile("s_waitcnt lgkmcnt(0)" ::: "memory");
; #pragma unroll
;       for (int d = 0; d < 8; ++d)
; #pragma unroll
;         for (int r = 0; r < 16; ++r) o[d][r] *= al_l[crow(r, hi)]; }
;     const int vb = vb0 + cur * A2_STAGE;
;     exp_pv256(o, p0, p1, vb, C, mnC, ps);
.LBB0_677:
	s_mul_i32 s4, s4, 0xc000
	s_waitcnt lgkmcnt(0)
	v_add_u32_e32 v0, s4, v221
	v_add_u32_e32 v248, v0, v233
	v_add_u32_e32 v249, v0, v234
	v_add_u32_e32 v250, v0, v235
	v_add_u32_e32 v0, v0, v236
	ds_read_b128 v[130:133], v248 offset:0
	ds_read_b128 v[134:137], v249 offset:0
	ds_read_b128 v[138:141], v250 offset:0
	ds_read_b128 v[142:145], v0 offset:0
	ds_read_b128 v[194:197], v248 offset:0x80
	ds_read_b128 v[198:201], v249 offset:0x80
	ds_read_b128 v[202:205], v250 offset:0x80
	ds_read_b128 v[206:209], v0 offset:0x80
	s_waitcnt lgkmcnt(7)
	s_nop 0
	v_mfma_f32_32x32x16_bf16 v[146:161], v[130:133], v[162:165], 0
	ds_read_b128 v[130:133], v248 offset:0x2000
	s_waitcnt lgkmcnt(7)
	s_nop 0
	v_mfma_f32_32x32x16_bf16 v[146:161], v[134:137], v[166:169], v[146:161]
	ds_read_b128 v[212:215], v249 offset:0x2000
	s_waitcnt lgkmcnt(7)
	s_nop 0
	v_mfma_f32_32x32x16_bf16 v[146:161], v[138:141], v[170:173], v[146:161]
	ds_read_b128 v[240:243], v250 offset:0x2000
	s_waitcnt lgkmcnt(7)
	s_nop 0
	v_mfma_f32_32x32x16_bf16 v[146:161], v[142:145], v[174:177], v[146:161]
	ds_read_b128 v[244:247], v0 offset:0x2000
	s_waitcnt lgkmcnt(7)
	s_nop 0
	v_mfma_f32_32x32x16_bf16 v[146:161], v[194:197], v[178:181], v[146:161]
	ds_read_b128 v[194:197], v248 offset:0x2080
	s_waitcnt lgkmcnt(7)
	s_nop 0
	v_mfma_f32_32x32x16_bf16 v[146:161], v[198:201], v[182:185], v[146:161]
	ds_read_b128 v[198:201], v249 offset:0x2080
	s_waitcnt lgkmcnt(7)
	s_nop 0
	v_mfma_f32_32x32x16_bf16 v[146:161], v[202:205], v[186:189], v[146:161]
	ds_read_b128 v[202:205], v250 offset:0x2080
	s_waitcnt lgkmcnt(7)
	s_nop 0
	v_mfma_f32_32x32x16_bf16 v[146:161], v[206:209], v[190:193], v[146:161]
	ds_read_b128 v[206:209], v0 offset:0x2080
	s_waitcnt lgkmcnt(7)
	s_nop 11
	v_max_f32_e32 v0, v147, v147
	v_max_f32_e32 v248, v146, v146
	v_mfma_f32_32x32x16_bf16 v[130:145], v[130:133], v[162:165], 0
	v_max_f32_e32 v0, v248, v0
	s_waitcnt lgkmcnt(6)
	s_nop 0
	v_mfma_f32_32x32x16_bf16 v[130:145], v[212:215], v[166:169], v[130:145]
	v_max3_f32 v0, v0, v148, v149
	s_waitcnt lgkmcnt(5)
	s_nop 0
	v_mfma_f32_32x32x16_bf16 v[130:145], v[240:243], v[170:173], v[130:145]
	v_max3_f32 v0, v0, v150, v151
	s_waitcnt lgkmcnt(4)
	s_nop 0
	v_mfma_f32_32x32x16_bf16 v[130:145], v[244:247], v[174:177], v[130:145]
	v_max3_f32 v0, v0, v152, v153
	s_waitcnt lgkmcnt(3)
	s_nop 0
	v_mfma_f32_32x32x16_bf16 v[130:145], v[194:197], v[178:181], v[130:145]
	v_max3_f32 v0, v0, v154, v155
	s_waitcnt lgkmcnt(2)
	s_nop 0
	v_mfma_f32_32x32x16_bf16 v[130:145], v[198:201], v[182:185], v[130:145]
	v_max3_f32 v0, v0, v156, v157
	s_waitcnt lgkmcnt(1)
	s_nop 0
	v_mfma_f32_32x32x16_bf16 v[130:145], v[202:205], v[186:189], v[130:145]
	v_max3_f32 v0, v0, v158, v159
	s_waitcnt lgkmcnt(0)
	s_nop 0
	v_mfma_f32_32x32x16_bf16 v[130:145], v[206:209], v[190:193], v[130:145]
	v_max3_f32 v0, v0, v160, v161
	v_mul_f32_e32 v248, 0xbe0293ee, v238
	s_nop 9
	v_max3_f32 v194, v130, v131, v132
	v_max3_f32 v195, v133, v134, v135
	v_max3_f32 v196, v136, v137, v138
	v_max3_f32 v197, v139, v140, v141
	v_max3_f32 v198, v142, v143, v144
	v_max3_f32 v194, v194, v195, v196
	v_max3_f32 v197, v197, v198, v145
	v_max3_f32 v0, v0, v194, v197
	v_mov_b32_e32 v194, v0
	s_nop 1
	v_permlane32_swap_b32_e32 v0, v194
	v_max_f32_e32 v194, v0, v194
	v_sub_f32_e32 v0, v194, v238
	v_cmp_ge_f32_e32 vcc, s93, v0
	s_cmp_eq_u64 vcc, exec
	v_mov_b32_e32 v0, 1.0
	s_cbranch_scc0 .LBB0_684
.LBB0_682:
	v_fmamk_f32 v146, v146, 0x3e0293ee, v248
	v_exp_f32_e32 v146, v146
	v_fmamk_f32 v147, v147, 0x3e0293ee, v248
	v_exp_f32_e32 v147, v147
	v_fmamk_f32 v148, v148, 0x3e0293ee, v248
	v_exp_f32_e32 v148, v148
	v_fmamk_f32 v149, v149, 0x3e0293ee, v248
	v_exp_f32_e32 v149, v149
	v_fmamk_f32 v150, v150, 0x3e0293ee, v248
	v_add_f32_e32 v194, 0, v146
	v_exp_f32_e32 v150, v150
	v_fmamk_f32 v151, v151, 0x3e0293ee, v248
	v_add_f32_e32 v194, v147, v194
	v_exp_f32_e32 v151, v151
	v_fmamk_f32 v152, v152, 0x3e0293ee, v248
	v_add_f32_e32 v194, v148, v194
	v_exp_f32_e32 v152, v152
	v_fmamk_f32 v153, v153, 0x3e0293ee, v248
	v_add_f32_e32 v194, v149, v194
	v_exp_f32_e32 v153, v153
	v_add_f32_e32 v194, v150, v194
	v_cvt_pk_bf16_f32 v146, v146, v147
	v_cvt_pk_bf16_f32 v147, v148, v149
	v_cvt_pk_bf16_f32 v148, v150, v151
	v_cvt_pk_bf16_f32 v149, v152, v153
	s_waitcnt lgkmcnt(0)
	v_add_f32_e32 v194, v151, v194
	s_add_i32 s34, s34, 1
	v_add_f32_e32 v194, v152, v194
	v_add_u32_e32 v249, s4, v237
	v_add_f32_e32 v250, v153, v194
	v_permlane32_swap_b32_e32 v146, v148
	v_permlane32_swap_b32_e32 v147, v149
	ds_read_b64_tr_b16 v[150:151], v249 offset:0
	ds_read_b64_tr_b16 v[152:153], v249 offset:0x800
	ds_read_b64_tr_b16 v[194:195], v249 offset:0x200
	ds_read_b64_tr_b16 v[196:197], v249 offset:0xa00
	ds_read_b64_tr_b16 v[198:199], v249 offset:0x400
	ds_read_b64_tr_b16 v[200:201], v249 offset:0xc00
	ds_read_b64_tr_b16 v[202:203], v249 offset:0x600
	ds_read_b64_tr_b16 v[204:205], v249 offset:0xe00
	v_add_u32_e32 v251, 0x4000, v249
	ds_read_b64_tr_b16 v[206:207], v251 offset:0
	ds_read_b64_tr_b16 v[208:209], v251 offset:0x800
	ds_read_b64_tr_b16 v[212:213], v251 offset:0x200
	ds_read_b64_tr_b16 v[214:215], v251 offset:0xa00
	ds_read_b64_tr_b16 v[240:241], v251 offset:0x400
	ds_read_b64_tr_b16 v[242:243], v251 offset:0xc00
	ds_read_b64_tr_b16 v[244:245], v251 offset:0x600
	ds_read_b64_tr_b16 v[246:247], v251 offset:0xe00
	s_waitcnt lgkmcnt(8)
; #define SBAR() __builtin_amdgcn_sched_barrier(0)
; #define LGKM_WAIT8() do { asm volatile("s_waitcnt lgkmcnt(8)" ::: "memory"); SBAR(); } while (0)
; #define LGKM_WAIT0() do { asm volatile("s_waitcnt lgkmcnt(0)" ::: "memory"); SBAR(); } while (0)
; #define EX4(P, B) do { _Pragma("unroll") for (int r_ = (B); r_ < (B) + 4; ++r_) { P[r_] = __builtin_amdgcn_exp2f(fmaf(P[r_], C, mnC)); ps += P[r_]; } } while (0)
; __device__ __forceinline__ void exp_pv256(f32x16 (&o)[8], f32x16& p0, f32x16& p1, int vb, float C, float mnC, float& ps) {
;   VG4 fa, fb; bf16x8 pa, pn;
;   ps = 0.f;
;   EX4(p0, 0); EX4(p0, 4); pa = pk4<0>(p0);
;   asm volatile("s_waitcnt lgkmcnt(0)" ::: "memory"); SBAR();
;   vg4_read<0>(fa, vb); vg4_read<0>(fb, vb + 16384);
;   LGKM_WAIT8(); vg4_mma<0>(o, fa, pa); EX4(p0, 8); SBAR();
;   vg4_read<1>(fa, vb); LGKM_WAIT8(); vg4_mma<1>(o, fb, pa); EX4(p0, 12); pn = pk4<8>(p0); SBAR();
;   vg4_read<1>(fb, vb + 16384); LGKM_WAIT8(); vg4_mma<0>(o, fa, pn); EX4(p1, 0); SBAR();
;   vg4_read<2>(fa, vb); LGKM_WAIT8(); vg4_mma<1>(o, fb, pn); EX4(p1, 4); pa = pk4<0>(p1); SBAR();
;   vg4_read<2>(fb, vb + 16384); LGKM_WAIT8(); vg4_mma<0>(o, fa, pa); EX4(p1, 8); SBAR();
;   vg4_read<3>(fa, vb); LGKM_WAIT8(); vg4_mma<1>(o, fb, pa); EX4(p1, 12); pn = pk4<8>(p1); SBAR();
;   vg4_read<3>(fb, vb + 16384); LGKM_WAIT8(); vg4_mma<0>(o, fa, pn); SBAR();
;   LGKM_WAIT0(); vg4_mma<1>(o, fb, pn);
	s_nop 0
	v_mfma_f32_32x32x16_bf16 v[2:17], v[146:149], v[150:153], v[2:17]
	v_fmamk_f32 v150, v154, 0x3e0293ee, v248
	v_exp_f32_e32 v252, v150
	v_fmamk_f32 v150, v155, 0x3e0293ee, v248
	v_exp_f32_e32 v231, v150
	v_fmamk_f32 v150, v156, 0x3e0293ee, v248
	v_exp_f32_e32 v232, v150
	v_fmamk_f32 v150, v157, 0x3e0293ee, v248
	v_mfma_f32_32x32x16_bf16 v[18:33], v[146:149], v[194:197], v[18:33]
	v_exp_f32_e32 v216, v150
	v_add_f32_e32 v150, v252, v250
	v_add_f32_e32 v150, v231, v150
	v_add_f32_e32 v150, v232, v150
	v_add_f32_e32 v217, v216, v150
	v_mfma_f32_32x32x16_bf16 v[34:49], v[146:149], v[198:201], v[34:49]
	v_mfma_f32_32x32x16_bf16 v[50:65], v[146:149], v[202:205], v[50:65]
	ds_read_b64_tr_b16 v[150:151], v249 offset:0x1000
	ds_read_b64_tr_b16 v[152:153], v249 offset:0x1800
	ds_read_b64_tr_b16 v[154:155], v249 offset:0x1200
	ds_read_b64_tr_b16 v[156:157], v249 offset:0x1a00
	ds_read_b64_tr_b16 v[194:195], v249 offset:0x1400
	ds_read_b64_tr_b16 v[196:197], v249 offset:0x1c00
	ds_read_b64_tr_b16 v[198:199], v249 offset:0x1600
	ds_read_b64_tr_b16 v[200:201], v249 offset:0x1e00
	s_waitcnt lgkmcnt(8)
	v_fmamk_f32 v158, v158, 0x3e0293ee, v248
	v_mfma_f32_32x32x16_bf16 v[66:81], v[146:149], v[206:209], v[66:81]
	v_exp_f32_e32 v202, v158
	v_fmamk_f32 v158, v159, 0x3e0293ee, v248
	v_exp_f32_e32 v203, v158
	v_fmamk_f32 v158, v160, 0x3e0293ee, v248
	v_exp_f32_e32 v204, v158
	v_fmamk_f32 v158, v161, 0x3e0293ee, v248
	v_exp_f32_e32 v161, v158
	v_mfma_f32_32x32x16_bf16 v[82:97], v[146:149], v[212:215], v[82:97]
	v_add_f32_e32 v158, v202, v217
	v_add_f32_e32 v158, v203, v158
	v_add_f32_e32 v158, v204, v158
	v_add_f32_e32 v217, v161, v158
	v_cvt_pk_bf16_f32 v158, v252, v231
	v_cvt_pk_bf16_f32 v159, v232, v216
	v_cvt_pk_bf16_f32 v160, v202, v203
	v_mfma_f32_32x32x16_bf16 v[98:113], v[146:149], v[240:243], v[98:113]
	v_cvt_pk_bf16_f32 v161, v204, v161
	v_permlane32_swap_b32_e32 v158, v160
	v_permlane32_swap_b32_e32 v159, v161
	v_mfma_f32_32x32x16_bf16 v[114:129], v[146:149], v[244:247], v[114:129]
	ds_read_b64_tr_b16 v[146:147], v251 offset:0x1000
	ds_read_b64_tr_b16 v[148:149], v251 offset:0x1800
	ds_read_b64_tr_b16 v[202:203], v251 offset:0x1200
	ds_read_b64_tr_b16 v[204:205], v251 offset:0x1a00
	ds_read_b64_tr_b16 v[206:207], v251 offset:0x1400
	ds_read_b64_tr_b16 v[208:209], v251 offset:0x1c00
	ds_read_b64_tr_b16 v[212:213], v251 offset:0x1600
	ds_read_b64_tr_b16 v[214:215], v251 offset:0x1e00
	s_waitcnt lgkmcnt(8)
	s_nop 0
	v_mfma_f32_32x32x16_bf16 v[2:17], v[158:161], v[150:153], v[2:17]
	v_fmamk_f32 v130, v130, 0x3e0293ee, v248
	v_exp_f32_e32 v216, v130
	v_fmamk_f32 v130, v131, 0x3e0293ee, v248
	v_exp_f32_e32 v231, v130
	v_fmamk_f32 v130, v132, 0x3e0293ee, v248
	v_exp_f32_e32 v232, v130
	v_fmamk_f32 v130, v133, 0x3e0293ee, v248
	v_mfma_f32_32x32x16_bf16 v[18:33], v[158:161], v[154:157], v[18:33]
	v_exp_f32_e32 v240, v130
	v_add_f32_e32 v130, v216, v217
	v_add_f32_e32 v130, v231, v130
	v_add_f32_e32 v130, v232, v130
	v_add_f32_e32 v217, v240, v130
	v_mfma_f32_32x32x16_bf16 v[34:49], v[158:161], v[194:197], v[34:49]
	v_mfma_f32_32x32x16_bf16 v[50:65], v[158:161], v[198:201], v[50:65]
	ds_read_b64_tr_b16 v[130:131], v249 offset:0x2000
	ds_read_b64_tr_b16 v[132:133], v249 offset:0x2800
	ds_read_b64_tr_b16 v[150:151], v249 offset:0x2200
	ds_read_b64_tr_b16 v[152:153], v249 offset:0x2a00
	ds_read_b64_tr_b16 v[154:155], v249 offset:0x2400
	ds_read_b64_tr_b16 v[156:157], v249 offset:0x2c00
	ds_read_b64_tr_b16 v[194:195], v249 offset:0x2600
	ds_read_b64_tr_b16 v[196:197], v249 offset:0x2e00
	s_waitcnt lgkmcnt(8)
	v_fmamk_f32 v134, v134, 0x3e0293ee, v248
	v_mfma_f32_32x32x16_bf16 v[66:81], v[158:161], v[146:149], v[66:81]
	v_exp_f32_e32 v146, v134
	v_fmamk_f32 v134, v135, 0x3e0293ee, v248
	v_exp_f32_e32 v147, v134
	v_fmamk_f32 v134, v136, 0x3e0293ee, v248
	v_exp_f32_e32 v148, v134
	v_fmamk_f32 v134, v137, 0x3e0293ee, v248
	v_exp_f32_e32 v137, v134
	v_mfma_f32_32x32x16_bf16 v[82:97], v[158:161], v[202:205], v[82:97]
	v_add_f32_e32 v134, v146, v217
	v_add_f32_e32 v134, v147, v134
	v_add_f32_e32 v134, v148, v134
	v_add_f32_e32 v217, v137, v134
	v_cvt_pk_bf16_f32 v134, v216, v231
	v_cvt_pk_bf16_f32 v135, v232, v240
	v_cvt_pk_bf16_f32 v136, v146, v147
	v_mfma_f32_32x32x16_bf16 v[98:113], v[158:161], v[206:209], v[98:113]
	v_cvt_pk_bf16_f32 v137, v148, v137
	v_permlane32_swap_b32_e32 v134, v136
	v_permlane32_swap_b32_e32 v135, v137
	v_mfma_f32_32x32x16_bf16 v[114:129], v[158:161], v[212:215], v[114:129]
	ds_read_b64_tr_b16 v[146:147], v251 offset:0x2000
	ds_read_b64_tr_b16 v[148:149], v251 offset:0x2800
	ds_read_b64_tr_b16 v[158:159], v251 offset:0x2200
	ds_read_b64_tr_b16 v[160:161], v251 offset:0x2a00
	ds_read_b64_tr_b16 v[198:199], v251 offset:0x2400
	ds_read_b64_tr_b16 v[200:201], v251 offset:0x2c00
	ds_read_b64_tr_b16 v[202:203], v251 offset:0x2600
	ds_read_b64_tr_b16 v[204:205], v251 offset:0x2e00
	s_waitcnt lgkmcnt(8)
; #define SBAR() __builtin_amdgcn_sched_barrier(0)
; __device__ __forceinline__ int crow(int r, int hi) { return (r & 3) + 8 * (r >> 2) + 4 * hi; }
; __device__ __forceinline__ float half_swap_sum(float v) { auto rr = __builtin_amdgcn_permlane32_swap(__float_as_uint(v), __float_as_uint(v), false, false); return __uint_as_float(rr[0]) + __uint_as_float(rr[1]); }
; #define LGKM_WAIT8() do { asm volatile("s_waitcnt lgkmcnt(8)" ::: "memory"); SBAR(); } while (0)
; #define LGKM_WAIT0() do { asm volatile("s_waitcnt lgkmcnt(0)" ::: "memory"); SBAR(); } while (0)
; #define EX4(P, B) do { _Pragma("unroll") for (int r_ = (B); r_ < (B) + 4; ++r_) { P[r_] = __builtin_amdgcn_exp2f(fmaf(P[r_], C, mnC)); ps += P[r_]; } } while (0)
; __device__ __forceinline__ void exp_pv256(f32x16 (&o)[8], f32x16& p0, f32x16& p1, int vb, float C, float mnC, float& ps) {
;     ...
;   vg4_read<2>(fa, vb); LGKM_WAIT8(); vg4_mma<1>(o, fb, pn); EX4(p1, 4); pa = pk4<0>(p1); SBAR();
;   vg4_read<2>(fb, vb + 16384); LGKM_WAIT8(); vg4_mma<0>(o, fa, pa); EX4(p1, 8); SBAR();
;   vg4_read<3>(fa, vb); LGKM_WAIT8(); vg4_mma<1>(o, fb, pa); EX4(p1, 12); pn = pk4<8>(p1); SBAR();
;   vg4_read<3>(fb, vb + 16384); LGKM_WAIT8(); vg4_mma<0>(o, fa, pn); SBAR();
;   LGKM_WAIT0(); vg4_mma<1>(o, fb, pn);
; template <int LD>
; __device__ __forceinline__ void attn256_body(const bf16_t* __restrict__ Qb, const bf16_t* __restrict__ Kh, const unsigned char* __restrict__ Vimg, int seq, char* lds, LAS unsigned char* ldsl,
;                                              f32x16 (&o)[8], float (&rli)[16]) {
;     ...
;     if (__builtin_expect(__all(pmax - m_reg <= ATT_THR / ATT_SCALE), 1)) { mn = m_reg; alpha = 1.f; }
;     else { mn = fmaxf(m_reg, pmax); alpha = __builtin_amdgcn_exp2f((m_reg - mn) * C); m_reg = mn; }
;     const float mnC = -mn * C; float ps;
;     if (__any(alpha < 1.f)) { if (hi == 0) al_l[r32] = alpha; asm volatile("s_waitcnt lgkmcnt(0)" ::: "memory");
; #pragma unroll
;       for (int d = 0; d < 8; ++d)
; #pragma unroll
;         for (int r = 0; r < 16; ++r) o[d][r] *= al_l[crow(r, hi)]; }
;     const int vb = vb0 + cur * A2_STAGE;
;     exp_pv256(o, p0, p1, vb, C, mnC, ps);
;     ps = half_swap_sum(ps);
;     l_reg = l_reg * alpha + ps;
;     asm volatile("s_waitcnt vmcnt(0)" ::: "memory"); __syncthreads();
;   }
	s_nop 0
	v_mfma_f32_32x32x16_bf16 v[2:17], v[134:137], v[130:133], v[2:17]
	v_fmamk_f32 v130, v138, 0x3e0293ee, v248
	v_exp_f32_e32 v206, v130
	v_fmamk_f32 v130, v139, 0x3e0293ee, v248
	v_exp_f32_e32 v207, v130
	v_fmamk_f32 v130, v140, 0x3e0293ee, v248
	v_exp_f32_e32 v208, v130
	v_fmamk_f32 v130, v141, 0x3e0293ee, v248
	v_mfma_f32_32x32x16_bf16 v[18:33], v[134:137], v[150:153], v[18:33]
	v_exp_f32_e32 v209, v130
	v_add_f32_e32 v130, v206, v217
	v_add_f32_e32 v130, v207, v130
	v_add_f32_e32 v130, v208, v130
	v_add_f32_e32 v212, v209, v130
	v_mfma_f32_32x32x16_bf16 v[34:49], v[134:137], v[154:157], v[34:49]
	v_mfma_f32_32x32x16_bf16 v[50:65], v[134:137], v[194:197], v[50:65]
	ds_read_b64_tr_b16 v[130:131], v249 offset:0x3000
	ds_read_b64_tr_b16 v[132:133], v249 offset:0x3800
	ds_read_b64_tr_b16 v[138:139], v249 offset:0x3200
	ds_read_b64_tr_b16 v[140:141], v249 offset:0x3a00
	ds_read_b64_tr_b16 v[150:151], v249 offset:0x3400
	ds_read_b64_tr_b16 v[152:153], v249 offset:0x3c00
	ds_read_b64_tr_b16 v[154:155], v249 offset:0x3600
	ds_read_b64_tr_b16 v[156:157], v249 offset:0x3e00
	s_waitcnt lgkmcnt(8)
	v_fmamk_f32 v142, v142, 0x3e0293ee, v248
	v_mfma_f32_32x32x16_bf16 v[66:81], v[134:137], v[146:149], v[66:81]
	v_exp_f32_e32 v146, v142
	v_fmamk_f32 v142, v143, 0x3e0293ee, v248
	v_exp_f32_e32 v147, v142
	v_fmamk_f32 v142, v144, 0x3e0293ee, v248
	v_exp_f32_e32 v148, v142
	v_fmac_f32_e32 v248, 0x3e0293ee, v145
	v_exp_f32_e32 v145, v248
	v_mfma_f32_32x32x16_bf16 v[82:97], v[134:137], v[158:161], v[82:97]
	v_add_f32_e32 v142, v146, v212
	v_add_f32_e32 v142, v147, v142
	v_add_f32_e32 v142, v148, v142
	v_add_f32_e32 v212, v145, v142
	v_cvt_pk_bf16_f32 v142, v206, v207
	v_cvt_pk_bf16_f32 v143, v208, v209
	v_cvt_pk_bf16_f32 v144, v146, v147
	v_mfma_f32_32x32x16_bf16 v[98:113], v[134:137], v[198:201], v[98:113]
	v_cvt_pk_bf16_f32 v145, v148, v145
	v_permlane32_swap_b32_e32 v142, v144
	v_permlane32_swap_b32_e32 v143, v145
	v_mfma_f32_32x32x16_bf16 v[114:129], v[134:137], v[202:205], v[114:129]
	ds_read_b64_tr_b16 v[134:135], v251 offset:0x3000
	ds_read_b64_tr_b16 v[136:137], v251 offset:0x3800
	ds_read_b64_tr_b16 v[146:147], v251 offset:0x3200
	ds_read_b64_tr_b16 v[148:149], v251 offset:0x3a00
	ds_read_b64_tr_b16 v[158:159], v251 offset:0x3400
	ds_read_b64_tr_b16 v[160:161], v251 offset:0x3c00
	ds_read_b64_tr_b16 v[194:195], v251 offset:0x3600
	ds_read_b64_tr_b16 v[196:197], v251 offset:0x3e00
	s_waitcnt lgkmcnt(8)
	s_nop 0
	v_mfma_f32_32x32x16_bf16 v[2:17], v[142:145], v[130:133], v[2:17]
	v_mfma_f32_32x32x16_bf16 v[18:33], v[142:145], v[138:141], v[18:33]
	v_mfma_f32_32x32x16_bf16 v[34:49], v[142:145], v[150:153], v[34:49]
	v_mfma_f32_32x32x16_bf16 v[50:65], v[142:145], v[154:157], v[50:65]
	s_waitcnt lgkmcnt(0)
	v_mfma_f32_32x32x16_bf16 v[66:81], v[142:145], v[134:137], v[66:81]
	v_mov_b32_e32 v130, v212
	s_nop 1
	v_permlane32_swap_b32_e32 v212, v130
	s_waitcnt vmcnt(0)
	v_add_f32_e32 v130, v212, v130
	v_fmac_f32_e32 v130, v239, v0
	v_lshl_add_u64 v[222:223], v[222:223], 0, s[30:31]
	v_mfma_f32_32x32x16_bf16 v[82:97], v[142:145], v[146:149], v[82:97]
	v_lshl_add_u64 v[224:225], v[224:225], 0, s[26:27]
	v_lshl_add_u64 v[226:227], v[226:227], 0, s[26:27]
	v_mov_b32_e32 v239, v130
	s_and_b32 s4, s34, 1
	s_cmpk_eq_i32 s34, 0xff
	s_cselect_b64 vcc, -1, 0
	s_cmpk_eq_i32 s34, 0x100
	s_waitcnt vmcnt(0) lgkmcnt(0)
	s_barrier
	v_mfma_f32_32x32x16_bf16 v[98:113], v[142:145], v[158:161], v[98:113]
	v_mfma_f32_32x32x16_bf16 v[114:129], v[142:145], v[194:197], v[114:129]
	s_cbranch_scc1 .LBB0_685
	s_cbranch_vccz .LBB0_676
	s_branch .LBB0_677
.LBB0_684:
	v_max_f32_e32 v0, v194, v194
	v_max_f32_e32 v194, v238, v238
	v_max_f32_e32 v194, v194, v0
	v_sub_f32_e32 v0, v238, v194
	v_mul_f32_e32 v0, 0x3e0293ee, v0
	v_exp_f32_e32 v0, v0
	v_mov_b32_e32 v238, v194
	v_mul_f32_e32 v248, 0xbe0293ee, v238
	v_cmp_gt_f32_e32 vcc, 1.0, v0
	s_cbranch_vccnz .LBB0_679
	s_branch .LBB0_682
